# v14
# baseline (speedup 1.0000x reference)
.LBB0_948:
	s_or_b64 exec, exec, s[8:9]
	s_waitcnt lgkmcnt(0)
	v_add_u32_e32 v72, v181, v176
	ds_read_b128 v[64:67], v72
	ds_read_b128 v[68:71], v72 offset:32
	s_add_u32 s8, s88, s14
	s_addc_u32 s9, s89, s15
	s_lshl_b64 s[6:7], s[12:13], 1
	s_waitcnt lgkmcnt(1)
	v_rcp_f32_e32 v73, v64
	v_rcp_f32_e32 v74, v65
	v_rcp_f32_e32 v75, v66
	v_rcp_f32_e32 v76, v67
	ds_read_b128 v[64:67], v72 offset:64
	s_add_u32 s6, s8, s6
	v_ashrrev_i32_e32 v181, 31, v180
	s_addc_u32 s7, s9, s7
	s_waitcnt lgkmcnt(1)
	v_rcp_f32_e32 v77, v68
	v_rcp_f32_e32 v78, v69
	v_rcp_f32_e32 v79, v70
	v_rcp_f32_e32 v80, v71
	ds_read_b128 v[68:71], v72 offset:96
	s_waitcnt lgkmcnt(1)
	v_rcp_f32_e32 v72, v64
	v_rcp_f32_e32 v81, v65
	v_lshlrev_b64 v[64:65], 12, v[180:181]
	v_lshl_add_u64 v[64:65], s[6:7], 0, v[64:65]
	v_lshlrev_b32_e32 v178, 1, v177
	v_rcp_f32_e32 v82, v66
	v_rcp_f32_e32 v83, v67
	v_lshlrev_b32_e32 v66, 14, v190
	v_lshl_add_u64 v[64:65], v[64:65], 0, v[178:179]
	v_mov_b32_e32 v67, v179
	v_lshl_add_u64 v[64:65], v[64:65], 0, v[66:67]
	s_mov_b64 s[6:7], 0xc4dbb00
	v_and_b32_e32 v92, 1, v177
	v_cmp_ne_u32_e64 s[100:101], 0, v92
	v_mul_u32_u24_e32 v92, 0x7e, v92
	v_add_co_u32_e32 v64, vcc, v64, v92
	s_nop 1
	v_addc_co_u32_e32 v65, vcc, 0, v65, vcc
	v_lshl_add_u64 v[66:67], v[64:65], 0, s[6:7]
	s_waitcnt lgkmcnt(0)
	v_rcp_f32_e32 v84, v68
	v_rcp_f32_e32 v85, v69
	v_rcp_f32_e32 v70, v70
	v_rcp_f32_e32 v71, v71
	v_mul_f32_e32 v0, v0, v73
	v_mul_f32_e32 v48, v48, v73
	v_mul_f32_e32 v32, v32, v73
	v_mul_f32_e32 v16, v16, v73
	v_mov_b32_dpp v88, v0 quad_perm:[1,0,3,2] row_mask:0xf bank_mask:0xf bound_ctrl:1
	v_mov_b32_dpp v89, v48 quad_perm:[1,0,3,2] row_mask:0xf bank_mask:0xf bound_ctrl:1
	v_mov_b32_dpp v90, v32 quad_perm:[1,0,3,2] row_mask:0xf bank_mask:0xf bound_ctrl:1
	v_mov_b32_dpp v91, v16 quad_perm:[1,0,3,2] row_mask:0xf bank_mask:0xf bound_ctrl:1
	s_mov_b32 s6, 0xc4db000
	v_add_co_u32_e32 v86, vcc, s6, v64
	v_cndmask_b32_e64 v90, v0, v90, s[100:101]
	v_cndmask_b32_e64 v88, v88, v32, s[100:101]
	v_addc_co_u32_e32 v87, vcc, 0, v65, vcc
	v_cndmask_b32_e64 v91, v48, v91, s[100:101]
	v_cndmask_b32_e64 v89, v89, v16, s[100:101]
	v_cvt_pk_bf16_f32 v0, v90, v88
	v_cvt_pk_bf16_f32 v48, v91, v89
	global_store_dword v[86:87], v0, off offset:2816
	global_store_dword v[86:87], v48, off offset:2880
	v_mul_f32_e32 v1, v1, v74
	v_mul_f32_e32 v49, v49, v74
	v_mul_f32_e32 v33, v33, v74
	v_mul_f32_e32 v17, v17, v74
	v_mov_b32_dpp v88, v1 quad_perm:[1,0,3,2] row_mask:0xf bank_mask:0xf bound_ctrl:1
	v_mov_b32_dpp v89, v49 quad_perm:[1,0,3,2] row_mask:0xf bank_mask:0xf bound_ctrl:1
	v_mov_b32_dpp v90, v33 quad_perm:[1,0,3,2] row_mask:0xf bank_mask:0xf bound_ctrl:1
	v_mov_b32_dpp v91, v17 quad_perm:[1,0,3,2] row_mask:0xf bank_mask:0xf bound_ctrl:1
	s_mov_b32 s6, 0xc4dc000
	v_add_co_u32_e32 v86, vcc, s6, v64
	v_cndmask_b32_e64 v90, v1, v90, s[100:101]
	v_cndmask_b32_e64 v88, v88, v33, s[100:101]
	v_addc_co_u32_e32 v87, vcc, 0, v65, vcc
	v_cndmask_b32_e64 v91, v49, v91, s[100:101]
	v_cndmask_b32_e64 v89, v89, v17, s[100:101]
	v_cvt_pk_bf16_f32 v1, v90, v88
	v_cvt_pk_bf16_f32 v49, v91, v89
	global_store_dword v[86:87], v1, off offset:2816
	global_store_dword v[86:87], v49, off offset:2880
	v_mul_f32_e32 v2, v2, v75
	v_mul_f32_e32 v50, v50, v75
	v_mul_f32_e32 v34, v34, v75
	v_mul_f32_e32 v18, v18, v75
	v_mov_b32_dpp v88, v2 quad_perm:[1,0,3,2] row_mask:0xf bank_mask:0xf bound_ctrl:1
	v_mov_b32_dpp v89, v50 quad_perm:[1,0,3,2] row_mask:0xf bank_mask:0xf bound_ctrl:1
	v_mov_b32_dpp v90, v34 quad_perm:[1,0,3,2] row_mask:0xf bank_mask:0xf bound_ctrl:1
	v_mov_b32_dpp v91, v18 quad_perm:[1,0,3,2] row_mask:0xf bank_mask:0xf bound_ctrl:1
	s_mov_b32 s6, 0xc4dd000
	v_add_co_u32_e32 v86, vcc, s6, v64
	v_cndmask_b32_e64 v90, v2, v90, s[100:101]
	v_cndmask_b32_e64 v88, v88, v34, s[100:101]
	v_addc_co_u32_e32 v87, vcc, 0, v65, vcc
	v_cndmask_b32_e64 v91, v50, v91, s[100:101]
	v_cndmask_b32_e64 v89, v89, v18, s[100:101]
	v_cvt_pk_bf16_f32 v2, v90, v88
	v_cvt_pk_bf16_f32 v50, v91, v89
	global_store_dword v[86:87], v2, off offset:2816
	global_store_dword v[86:87], v50, off offset:2880
	v_mul_f32_e32 v3, v3, v76
	v_mul_f32_e32 v51, v51, v76
	v_mul_f32_e32 v35, v35, v76
	v_mul_f32_e32 v19, v19, v76
	v_mov_b32_dpp v88, v3 quad_perm:[1,0,3,2] row_mask:0xf bank_mask:0xf bound_ctrl:1
	v_mov_b32_dpp v89, v51 quad_perm:[1,0,3,2] row_mask:0xf bank_mask:0xf bound_ctrl:1
	v_mov_b32_dpp v90, v35 quad_perm:[1,0,3,2] row_mask:0xf bank_mask:0xf bound_ctrl:1
	v_mov_b32_dpp v91, v19 quad_perm:[1,0,3,2] row_mask:0xf bank_mask:0xf bound_ctrl:1
	s_mov_b32 s6, 0xc4de000
	v_add_co_u32_e32 v86, vcc, s6, v64
	v_cndmask_b32_e64 v90, v3, v90, s[100:101]
	v_cndmask_b32_e64 v88, v88, v35, s[100:101]
	v_addc_co_u32_e32 v87, vcc, 0, v65, vcc
	v_cndmask_b32_e64 v91, v51, v91, s[100:101]
	v_cndmask_b32_e64 v89, v89, v19, s[100:101]
	v_cvt_pk_bf16_f32 v3, v90, v88
	v_cvt_pk_bf16_f32 v51, v91, v89
	global_store_dword v[86:87], v3, off offset:2816
	global_store_dword v[86:87], v51, off offset:2880
	v_mul_f32_e32 v4, v4, v77
	v_mul_f32_e32 v52, v52, v77
	v_mul_f32_e32 v36, v36, v77
	v_mul_f32_e32 v20, v20, v77
	v_mov_b32_dpp v88, v4 quad_perm:[1,0,3,2] row_mask:0xf bank_mask:0xf bound_ctrl:1
	v_mov_b32_dpp v89, v52 quad_perm:[1,0,3,2] row_mask:0xf bank_mask:0xf bound_ctrl:1
	v_mov_b32_dpp v90, v36 quad_perm:[1,0,3,2] row_mask:0xf bank_mask:0xf bound_ctrl:1
	v_mov_b32_dpp v91, v20 quad_perm:[1,0,3,2] row_mask:0xf bank_mask:0xf bound_ctrl:1
	s_mov_b32 s6, 0xc4e3000
	v_add_co_u32_e32 v86, vcc, s6, v64
	v_cndmask_b32_e64 v90, v4, v90, s[100:101]
	v_cndmask_b32_e64 v88, v88, v36, s[100:101]
	v_addc_co_u32_e32 v87, vcc, 0, v65, vcc
	v_cndmask_b32_e64 v91, v52, v91, s[100:101]
	v_cndmask_b32_e64 v89, v89, v20, s[100:101]
	v_cvt_pk_bf16_f32 v4, v90, v88
	v_cvt_pk_bf16_f32 v52, v91, v89
	global_store_dword v[86:87], v4, off offset:2816
	global_store_dword v[86:87], v52, off offset:2880
	v_mul_f32_e32 v5, v5, v78
	v_mul_f32_e32 v53, v53, v78
	v_mul_f32_e32 v37, v37, v78
	v_mul_f32_e32 v21, v21, v78
	v_mov_b32_dpp v88, v5 quad_perm:[1,0,3,2] row_mask:0xf bank_mask:0xf bound_ctrl:1
	v_mov_b32_dpp v89, v53 quad_perm:[1,0,3,2] row_mask:0xf bank_mask:0xf bound_ctrl:1
	v_mov_b32_dpp v90, v37 quad_perm:[1,0,3,2] row_mask:0xf bank_mask:0xf bound_ctrl:1
	v_mov_b32_dpp v91, v21 quad_perm:[1,0,3,2] row_mask:0xf bank_mask:0xf bound_ctrl:1
	s_mov_b32 s6, 0xc4e4000
	v_add_co_u32_e32 v86, vcc, s6, v64
	v_cndmask_b32_e64 v90, v5, v90, s[100:101]
	v_cndmask_b32_e64 v88, v88, v37, s[100:101]
	v_addc_co_u32_e32 v87, vcc, 0, v65, vcc
	v_cndmask_b32_e64 v91, v53, v91, s[100:101]
	v_cndmask_b32_e64 v89, v89, v21, s[100:101]
	v_cvt_pk_bf16_f32 v5, v90, v88
	v_cvt_pk_bf16_f32 v53, v91, v89
	global_store_dword v[86:87], v5, off offset:2816
	global_store_dword v[86:87], v53, off offset:2880
	v_mul_f32_e32 v6, v6, v79
	v_mul_f32_e32 v54, v54, v79
	v_mul_f32_e32 v38, v38, v79
	v_mul_f32_e32 v22, v22, v79
	v_mov_b32_dpp v88, v6 quad_perm:[1,0,3,2] row_mask:0xf bank_mask:0xf bound_ctrl:1
	v_mov_b32_dpp v89, v54 quad_perm:[1,0,3,2] row_mask:0xf bank_mask:0xf bound_ctrl:1
	v_mov_b32_dpp v90, v38 quad_perm:[1,0,3,2] row_mask:0xf bank_mask:0xf bound_ctrl:1
	v_mov_b32_dpp v91, v22 quad_perm:[1,0,3,2] row_mask:0xf bank_mask:0xf bound_ctrl:1
	s_mov_b32 s6, 0xc4e5000
	v_add_co_u32_e32 v86, vcc, s6, v64
	v_cndmask_b32_e64 v90, v6, v90, s[100:101]
	v_cndmask_b32_e64 v88, v88, v38, s[100:101]
	v_addc_co_u32_e32 v87, vcc, 0, v65, vcc
	v_cndmask_b32_e64 v91, v54, v91, s[100:101]
	v_cndmask_b32_e64 v89, v89, v22, s[100:101]
	v_cvt_pk_bf16_f32 v6, v90, v88
	v_cvt_pk_bf16_f32 v54, v91, v89
	global_store_dword v[86:87], v6, off offset:2816
	global_store_dword v[86:87], v54, off offset:2880
	v_mul_f32_e32 v7, v7, v80
	v_mul_f32_e32 v55, v55, v80
	v_mul_f32_e32 v39, v39, v80
	v_mul_f32_e32 v23, v23, v80
	v_mov_b32_dpp v88, v7 quad_perm:[1,0,3,2] row_mask:0xf bank_mask:0xf bound_ctrl:1
	v_mov_b32_dpp v89, v55 quad_perm:[1,0,3,2] row_mask:0xf bank_mask:0xf bound_ctrl:1
	v_mov_b32_dpp v90, v39 quad_perm:[1,0,3,2] row_mask:0xf bank_mask:0xf bound_ctrl:1
	v_mov_b32_dpp v91, v23 quad_perm:[1,0,3,2] row_mask:0xf bank_mask:0xf bound_ctrl:1
	s_mov_b32 s6, 0xc4e6000
	v_add_co_u32_e32 v86, vcc, s6, v64
	v_cndmask_b32_e64 v90, v7, v90, s[100:101]
	v_cndmask_b32_e64 v88, v88, v39, s[100:101]
	v_addc_co_u32_e32 v87, vcc, 0, v65, vcc
	v_cndmask_b32_e64 v91, v55, v91, s[100:101]
	v_cndmask_b32_e64 v89, v89, v23, s[100:101]
	v_cvt_pk_bf16_f32 v7, v90, v88
	v_cvt_pk_bf16_f32 v55, v91, v89
	global_store_dword v[86:87], v7, off offset:2816
	global_store_dword v[86:87], v55, off offset:2880
	v_mul_f32_e32 v8, v8, v72
	v_mul_f32_e32 v56, v56, v72
	v_mul_f32_e32 v40, v40, v72
	v_mul_f32_e32 v24, v24, v72
	v_mov_b32_dpp v88, v8 quad_perm:[1,0,3,2] row_mask:0xf bank_mask:0xf bound_ctrl:1
	v_mov_b32_dpp v89, v56 quad_perm:[1,0,3,2] row_mask:0xf bank_mask:0xf bound_ctrl:1
	v_mov_b32_dpp v90, v40 quad_perm:[1,0,3,2] row_mask:0xf bank_mask:0xf bound_ctrl:1
	v_mov_b32_dpp v91, v24 quad_perm:[1,0,3,2] row_mask:0xf bank_mask:0xf bound_ctrl:1
	s_mov_b32 s6, 0xc4eb000
	v_add_co_u32_e32 v86, vcc, s6, v64
	v_cndmask_b32_e64 v90, v8, v90, s[100:101]
	v_cndmask_b32_e64 v88, v88, v40, s[100:101]
	v_addc_co_u32_e32 v87, vcc, 0, v65, vcc
	v_cndmask_b32_e64 v91, v56, v91, s[100:101]
	v_cndmask_b32_e64 v89, v89, v24, s[100:101]
	v_cvt_pk_bf16_f32 v8, v90, v88
	v_cvt_pk_bf16_f32 v56, v91, v89
	global_store_dword v[86:87], v8, off offset:2816
	global_store_dword v[86:87], v56, off offset:2880
	v_mul_f32_e32 v9, v9, v81
	v_mul_f32_e32 v57, v57, v81
	v_mul_f32_e32 v41, v41, v81
	v_mul_f32_e32 v25, v25, v81
	v_mov_b32_dpp v88, v9 quad_perm:[1,0,3,2] row_mask:0xf bank_mask:0xf bound_ctrl:1
	v_mov_b32_dpp v89, v57 quad_perm:[1,0,3,2] row_mask:0xf bank_mask:0xf bound_ctrl:1
	v_mov_b32_dpp v90, v41 quad_perm:[1,0,3,2] row_mask:0xf bank_mask:0xf bound_ctrl:1
	v_mov_b32_dpp v91, v25 quad_perm:[1,0,3,2] row_mask:0xf bank_mask:0xf bound_ctrl:1
	s_mov_b32 s6, 0xc4ec000
	v_add_co_u32_e32 v86, vcc, s6, v64
	v_cndmask_b32_e64 v90, v9, v90, s[100:101]
	v_cndmask_b32_e64 v88, v88, v41, s[100:101]
	v_addc_co_u32_e32 v87, vcc, 0, v65, vcc
	v_cndmask_b32_e64 v91, v57, v91, s[100:101]
	v_cndmask_b32_e64 v89, v89, v25, s[100:101]
	v_cvt_pk_bf16_f32 v9, v90, v88
	v_cvt_pk_bf16_f32 v57, v91, v89
	global_store_dword v[86:87], v9, off offset:2816
	global_store_dword v[86:87], v57, off offset:2880
	v_mul_f32_e32 v10, v10, v82
	v_mul_f32_e32 v58, v58, v82
	v_mul_f32_e32 v42, v42, v82
	v_mul_f32_e32 v26, v26, v82
	v_mov_b32_dpp v88, v10 quad_perm:[1,0,3,2] row_mask:0xf bank_mask:0xf bound_ctrl:1
	v_mov_b32_dpp v89, v58 quad_perm:[1,0,3,2] row_mask:0xf bank_mask:0xf bound_ctrl:1
	v_mov_b32_dpp v90, v42 quad_perm:[1,0,3,2] row_mask:0xf bank_mask:0xf bound_ctrl:1
	v_mov_b32_dpp v91, v26 quad_perm:[1,0,3,2] row_mask:0xf bank_mask:0xf bound_ctrl:1
	s_mov_b32 s6, 0xc4ed000
	v_add_co_u32_e32 v86, vcc, s6, v64
	v_cndmask_b32_e64 v90, v10, v90, s[100:101]
	v_cndmask_b32_e64 v88, v88, v42, s[100:101]
	v_addc_co_u32_e32 v87, vcc, 0, v65, vcc
	v_cndmask_b32_e64 v91, v58, v91, s[100:101]
	v_cndmask_b32_e64 v89, v89, v26, s[100:101]
	v_cvt_pk_bf16_f32 v10, v90, v88
	v_cvt_pk_bf16_f32 v58, v91, v89
	global_store_dword v[86:87], v10, off offset:2816
	global_store_dword v[86:87], v58, off offset:2880
	v_mul_f32_e32 v11, v11, v83
	v_mul_f32_e32 v59, v59, v83
	v_mul_f32_e32 v43, v43, v83
	v_mul_f32_e32 v27, v27, v83
	v_mov_b32_dpp v88, v11 quad_perm:[1,0,3,2] row_mask:0xf bank_mask:0xf bound_ctrl:1
	v_mov_b32_dpp v89, v59 quad_perm:[1,0,3,2] row_mask:0xf bank_mask:0xf bound_ctrl:1
	v_mov_b32_dpp v90, v43 quad_perm:[1,0,3,2] row_mask:0xf bank_mask:0xf bound_ctrl:1
	v_mov_b32_dpp v91, v27 quad_perm:[1,0,3,2] row_mask:0xf bank_mask:0xf bound_ctrl:1
	s_mov_b32 s6, 0xc4ee000
	v_add_co_u32_e32 v86, vcc, s6, v64
	v_cndmask_b32_e64 v90, v11, v90, s[100:101]
	v_cndmask_b32_e64 v88, v88, v43, s[100:101]
	v_addc_co_u32_e32 v87, vcc, 0, v65, vcc
	v_cndmask_b32_e64 v91, v59, v91, s[100:101]
	v_cndmask_b32_e64 v89, v89, v27, s[100:101]
	v_cvt_pk_bf16_f32 v11, v90, v88
	v_cvt_pk_bf16_f32 v59, v91, v89
	global_store_dword v[86:87], v11, off offset:2816
	global_store_dword v[86:87], v59, off offset:2880
	v_mul_f32_e32 v12, v12, v84
	v_mul_f32_e32 v60, v60, v84
	v_mul_f32_e32 v44, v44, v84
	v_mul_f32_e32 v28, v28, v84
	v_mov_b32_dpp v88, v12 quad_perm:[1,0,3,2] row_mask:0xf bank_mask:0xf bound_ctrl:1
	v_mov_b32_dpp v89, v60 quad_perm:[1,0,3,2] row_mask:0xf bank_mask:0xf bound_ctrl:1
	v_mov_b32_dpp v90, v44 quad_perm:[1,0,3,2] row_mask:0xf bank_mask:0xf bound_ctrl:1
	v_mov_b32_dpp v91, v28 quad_perm:[1,0,3,2] row_mask:0xf bank_mask:0xf bound_ctrl:1
	s_mov_b32 s6, 0xc4f3000
	v_add_co_u32_e32 v86, vcc, s6, v64
	v_cndmask_b32_e64 v90, v12, v90, s[100:101]
	v_cndmask_b32_e64 v88, v88, v44, s[100:101]
	v_addc_co_u32_e32 v87, vcc, 0, v65, vcc
	v_cndmask_b32_e64 v91, v60, v91, s[100:101]
	v_cndmask_b32_e64 v89, v89, v28, s[100:101]
	v_cvt_pk_bf16_f32 v12, v90, v88
	v_cvt_pk_bf16_f32 v60, v91, v89
	global_store_dword v[86:87], v12, off offset:2816
	global_store_dword v[86:87], v60, off offset:2880
	v_mul_f32_e32 v13, v13, v85
	v_mul_f32_e32 v61, v61, v85
	v_mul_f32_e32 v45, v45, v85
	v_mul_f32_e32 v29, v29, v85
	v_mov_b32_dpp v88, v13 quad_perm:[1,0,3,2] row_mask:0xf bank_mask:0xf bound_ctrl:1
	v_mov_b32_dpp v89, v61 quad_perm:[1,0,3,2] row_mask:0xf bank_mask:0xf bound_ctrl:1
	v_mov_b32_dpp v90, v45 quad_perm:[1,0,3,2] row_mask:0xf bank_mask:0xf bound_ctrl:1
	v_mov_b32_dpp v91, v29 quad_perm:[1,0,3,2] row_mask:0xf bank_mask:0xf bound_ctrl:1
	s_mov_b32 s6, 0xc4f4000
	v_add_co_u32_e32 v86, vcc, s6, v64
	v_cndmask_b32_e64 v90, v13, v90, s[100:101]
	v_cndmask_b32_e64 v88, v88, v45, s[100:101]
	v_addc_co_u32_e32 v87, vcc, 0, v65, vcc
	v_cndmask_b32_e64 v91, v61, v91, s[100:101]
	v_cndmask_b32_e64 v89, v89, v29, s[100:101]
	v_cvt_pk_bf16_f32 v13, v90, v88
	v_cvt_pk_bf16_f32 v61, v91, v89
	global_store_dword v[86:87], v13, off offset:2816
	global_store_dword v[86:87], v61, off offset:2880
	v_mul_f32_e32 v14, v14, v70
	v_mul_f32_e32 v62, v62, v70
	v_mul_f32_e32 v46, v46, v70
	v_mul_f32_e32 v30, v30, v70
	v_mov_b32_dpp v88, v14 quad_perm:[1,0,3,2] row_mask:0xf bank_mask:0xf bound_ctrl:1
	v_mov_b32_dpp v89, v62 quad_perm:[1,0,3,2] row_mask:0xf bank_mask:0xf bound_ctrl:1
	v_mov_b32_dpp v90, v46 quad_perm:[1,0,3,2] row_mask:0xf bank_mask:0xf bound_ctrl:1
	v_mov_b32_dpp v91, v30 quad_perm:[1,0,3,2] row_mask:0xf bank_mask:0xf bound_ctrl:1
	s_mov_b32 s6, 0xc4f5000
	v_add_co_u32_e32 v86, vcc, s6, v64
	v_cndmask_b32_e64 v90, v14, v90, s[100:101]
	v_cndmask_b32_e64 v88, v88, v46, s[100:101]
	v_addc_co_u32_e32 v87, vcc, 0, v65, vcc
	v_cndmask_b32_e64 v91, v62, v91, s[100:101]
	v_cndmask_b32_e64 v89, v89, v30, s[100:101]
	v_cvt_pk_bf16_f32 v14, v90, v88
	v_cvt_pk_bf16_f32 v62, v91, v89
	global_store_dword v[86:87], v14, off offset:2816
	global_store_dword v[86:87], v62, off offset:2880
	v_mul_f32_e32 v15, v15, v71
	v_mul_f32_e32 v63, v63, v71
	v_mul_f32_e32 v47, v47, v71
	v_mul_f32_e32 v31, v31, v71
	v_mov_b32_dpp v88, v15 quad_perm:[1,0,3,2] row_mask:0xf bank_mask:0xf bound_ctrl:1
	v_mov_b32_dpp v89, v63 quad_perm:[1,0,3,2] row_mask:0xf bank_mask:0xf bound_ctrl:1
	v_mov_b32_dpp v90, v47 quad_perm:[1,0,3,2] row_mask:0xf bank_mask:0xf bound_ctrl:1
	v_mov_b32_dpp v91, v31 quad_perm:[1,0,3,2] row_mask:0xf bank_mask:0xf bound_ctrl:1
	s_mov_b32 s6, 0xc4f6000
	v_add_co_u32_e32 v86, vcc, s6, v64
	v_cndmask_b32_e64 v90, v15, v90, s[100:101]
	v_cndmask_b32_e64 v88, v88, v47, s[100:101]
	v_addc_co_u32_e32 v87, vcc, 0, v65, vcc
	v_cndmask_b32_e64 v91, v63, v91, s[100:101]
	v_cndmask_b32_e64 v89, v89, v31, s[100:101]
	v_cvt_pk_bf16_f32 v15, v90, v88
	v_cvt_pk_bf16_f32 v63, v91, v89
	global_store_dword v[86:87], v15, off offset:2816
	global_store_dword v[86:87], v63, off offset:2880
	s_mov_b64 s[6:7], 0
	s_waitcnt lgkmcnt(0)
	s_barrier
